# same as the previous version, the two halves are chosen by bit 4 of the workgroup index instead of bit 3
# speedup vs baseline: 1.0248x; 1.0008x over previous
.LBB0_5:
	s_or_b64 exec, exec, s[6:7]
	s_load_dwordx16 s[8:23], s[0:1], 0x40
	s_load_dwordx16 s[80:95], s[0:1], 0x80
	s_cmp_lt_i32 s68, 1
	s_cselect_b64 s[6:7], -1, 0
	s_cmp_gt_i32 s69, 0
	s_waitcnt lgkmcnt(0)
	v_writelane_b32 v240, s8, 6
	s_nop 1
	v_writelane_b32 v240, s9, 7
	v_writelane_b32 v240, s10, 8
	v_writelane_b32 v240, s11, 9
	v_writelane_b32 v240, s12, 10
	v_writelane_b32 v240, s13, 11
	v_writelane_b32 v240, s14, 12
	v_writelane_b32 v240, s15, 13
	v_writelane_b32 v240, s16, 14
	v_writelane_b32 v240, s17, 15
	v_writelane_b32 v240, s18, 16
	v_writelane_b32 v240, s19, 17
	v_writelane_b32 v240, s20, 18
	v_writelane_b32 v240, s21, 19
	v_writelane_b32 v240, s22, 20
	v_writelane_b32 v240, s23, 21
	s_cselect_b64 s[8:9], -1, 0
	s_and_b64 s[52:53], s[6:7], s[8:9]
	s_andn2_b64 vcc, exec, s[52:53]
	s_cbranch_vccnz .LBB0_68
	s_cmpk_gt_i32 s2, 0x510
	s_cbranch_scc1 .LBB0_68
	v_add_u32_e32 v3, -1, v1
	v_and_b32_e32 v2, 63, v1
	v_and_b32_e32 v3, 15, v3
	v_lshlrev_b32_e32 v54, 2, v2
	v_cvt_f32_ubyte0_e32 v3, v3
	v_mov_b32_e32 v102, 0x38d1b717
	v_add_u32_e32 v101, 0, v54
	v_fmac_f32_e32 v102, 0x3f7fff90, v3
	v_and_b32_e32 v3, 0x3c0, v1
	v_and_b32_e32 v107, 31, v1
	v_and_b32_e32 v5, 0x3e0, v1
	v_lshl_add_u32 v106, v3, 2, v101
	v_lshrrev_b32_e32 v3, 5, v1
	v_lshlrev_b32_e32 v5, 2, v5
	v_lshlrev_b32_e32 v6, 2, v107
	s_add_u32 s54, s66, 0x1400000
	v_lshl_add_u32 v108, v3, 8, 0
	v_add3_u32 v109, 0, v5, v6
	v_mul_u32_u24_e32 v5, 0x700, v3
	s_addc_u32 s55, s67, 0
	v_add3_u32 v110, v108, v5, v6
	v_mul_u32_u24_e32 v5, 0x1800, v3
	s_add_u32 s28, s66, 0x1600000
	v_or_b32_e32 v111, v5, v107
	v_lshlrev_b32_e32 v5, 4, v1
	s_addc_u32 s29, s67, 0
	s_load_dwordx16 s[12:27], s[0:1], 0x0
	v_and_b32_e32 v8, 0x3f0, v5
	v_lshlrev_b32_e32 v5, 5, v1
	s_add_u32 s96, s66, 0x1800000
	v_lshrrev_b32_e32 v113, 1, v1
	v_and_b32_e32 v56, 32, v5
	s_addc_u32 s97, s67, 0
	v_mov_b32_e32 v55, 0
	v_lshlrev_b32_e32 v5, 2, v113
	v_mul_u32_u24_e32 v7, 0x404, v56
	s_add_u32 s72, s66, 0x1a00000
	v_lshlrev_b32_e32 v4, 2, v1
	v_add3_u32 v114, 0, v5, v7
	s_addc_u32 s73, s67, 0
	v_mov_b32_e32 v9, v55
	v_mov_b32_e32 v5, v55
	v_writelane_b32 v240, s3, 22
	v_add_u32_e32 v112, 0, v8
	s_add_u32 s33, s66, 0x1a80000
	v_lshl_add_u64 v[66:67], s[94:95], 0, v[8:9]
	v_lshl_add_u64 v[68:69], s[92:93], 0, v[8:9]
	v_lshl_add_u64 v[70:71], s[90:91], 0, v[8:9]
	s_waitcnt lgkmcnt(0)
	v_lshl_add_u64 v[72:73], s[26:27], 0, v[8:9]
	v_lshl_add_u64 v[8:9], s[66:67], 0, v[4:5]
	s_mov_b64 s[8:9], 0x1a20000
	v_lshrrev_b32_e32 v57, 6, v1
	s_movk_i32 s6, 0xa0
	v_mul_u32_u24_e32 v3, 0x60000, v3
	s_addc_u32 s3, s67, 0
	v_readlane_b32 s36, v240, 6
	v_mov_b32_e32 v7, v55
	v_lshl_add_u64 v[82:83], v[8:9], 0, s[8:9]
	s_movk_i32 s8, 0xf000
	v_mad_u32_u24 v104, v57, s6, 0
	s_movk_i32 s6, 0x60
	s_add_u32 s57, s66, 0x1a40000
	v_readlane_b32 s37, v240, 7
	v_readlane_b32 s44, v240, 14
	v_readlane_b32 s45, v240, 15
	v_readlane_b32 s46, v240, 16
	v_readlane_b32 s47, v240, 17
	v_readlane_b32 s48, v240, 18
	v_readlane_b32 s49, v240, 19
	v_readlane_b32 s50, v240, 20
	v_readlane_b32 s51, v240, 21
	v_lshl_add_u64 v[6:7], s[22:23], 0, v[6:7]
	v_lshlrev_b32_e32 v10, 2, v3
	v_mov_b32_e32 v11, v55
	v_lshl_add_u32 v3, v57, 8, 0
	v_lshl_add_u64 v[8:9], s[18:19], 0, v[4:5]
	s_mov_b32 s9, -1
	s_mov_b32 s18, 0x54442d18
	v_or_b32_e32 v100, 0xffffc000, v57
	v_mul_u32_u24_e32 v103, 0xa0, v57
	v_add_u32_e32 v105, 0, v4
	v_cmp_gt_u32_e64 s[6:7], s6, v1
	s_addc_u32 s74, s67, 0
	v_lshl_add_u64 v[58:59], s[46:47], 0, v[54:55]
	v_lshl_add_u64 v[60:61], s[84:85], 0, v[54:55]
	v_lshl_add_u64 v[62:63], s[50:51], 0, v[54:55]
	v_lshl_add_u64 v[64:65], s[82:83], 0, v[54:55]
	v_lshl_add_u64 v[74:75], s[44:45], 0, v[54:55]
	s_movk_i32 s56, 0x1000
	v_add_u32_e32 v115, 0x1000, v3
	v_lshl_add_u64 v[76:77], s[48:49], 0, v[54:55]
	v_add_u32_e32 v116, 0x2000, v3
	v_lshl_add_u64 v[78:79], s[80:81], 0, v[54:55]
	v_lshl_add_u64 v[80:81], s[36:37], 0, v[4:5]
	v_lshl_add_u64 v[84:85], v[8:9], 0, s[8:9]
	v_lshl_add_u64 v[86:87], s[20:21], 0, v[4:5]
	s_mov_b32 s19, 0x401921fb
	v_lshlrev_b32_e32 v88, 1, v2
	v_mul_u32_u24_e32 v117, 0x404, v57
	v_add_u32_e32 v118, 0xfffffe00, v1
	v_mov_b32_e32 v119, 0x1000
	v_mov_b32_e32 v120, 0x100
	v_mov_b32_e32 v121, 0xffffff08
	v_mov_b32_e32 v122, 0x80000
	v_mov_b32_e32 v123, 0x8000
	v_mov_b32_e32 v124, 0x7f800000
	v_lshl_add_u64 v[90:91], v[6:7], 0, v[10:11]
	s_mov_b32 s21, 0x10e000
	s_mov_b32 s20, 0x114000
	s_mov_b32 s22, 0x11a000
	s_mov_b32 s58, 0x120000
	s_mov_b32 s59, 0x126000
	s_mov_b32 s60, 0x12c000
	s_mov_b32 s61, 0x132000
	s_mov_b32 s62, 0x138000
	s_mov_b32 s63, 0x13e000
	s_mov_b32 s75, 0x144000
	s_mov_b32 s76, 0x14a000
	s_mov_b32 s77, 0x150000
	s_mov_b32 s78, 0x156000
	s_mov_b32 s79, 0x15c000
	s_mov_b32 s80, 0x162000
	s_mov_b32 s81, 0x168000
	s_mov_b32 s82, 0x16e000
	s_mov_b32 s83, 0x174000
	s_mov_b32 s84, 0x17a000
	s_mov_b32 s85, 0xa000
	s_mov_b32 s90, s2
	s_mov_b32 s32, s70
	s_cmpk_lg_u32 s70, 0x100
	s_cbranch_scc1 .Lp0_order
	s_bitcmp1_b32 s2, 4
	s_cbranch_scc0 .Lp0_order
	s_movk_i32 s32, 0xff00
	s_addk_i32 s90, 0x400
	s_cmpk_gt_u32 s2, 16
	s_cbranch_scc1 .Lp0_order
	s_addk_i32 s90, 0x100

.LBB0_207:
.LBB0_208:
	s_cmp_lt_i32 s68, 3
	s_cselect_b64 s[8:9], -1, 0
	s_and_b64 s[8:9], s[8:9], s[6:7]
	s_andn2_b64 vcc, exec, s[8:9]
	v_writelane_b32 v240, s0, 22
	s_nop 1
	v_writelane_b32 v240, s1, 23
	s_cbranch_vccnz .LBB0_225
	s_cmpk_lg_u32 s70, 0x100
	s_cbranch_scc1 .Lp2_tiles
	s_bitcmp1_b32 s2, 4
	s_cbranch_scc1 .Lpf_begin

.LBB0_224:
	s_waitcnt vmcnt(0)
	v_readlane_b32 s0, v240, 22
	v_readlane_b32 s1, v240, 23
	s_barrier
	s_cmpk_lg_u32 s70, 0x100
	s_cbranch_scc1 .Lpf_begin
	s_bitcmp1_b32 s2, 4
	s_cbranch_scc1 .Lpf_done

.Lpf_end:
	s_cmpk_lg_u32 s70, 0x100
	s_cbranch_scc1 .Lpf_done
	s_bitcmp1_b32 s2, 4
	s_cbranch_scc1 .Lp2_tiles

.LBB0_292:
.LBB0_293:
	s_cmp_lt_i32 s68, 4
	s_cselect_b64 s[8:9], -1, 0
	s_and_b64 s[18:19], s[8:9], s[6:7]
	s_andn2_b64 vcc, exec, s[18:19]
	s_cbranch_vccnz .LBB0_510
	s_cmpk_gt_i32 s2, 0x1ff
	s_cbranch_scc1 .LBB0_510
	v_bfe_u32 v113, v1, 5, 1
	v_lshl_or_b32 v3, v1, 8, v1
	v_lshlrev_b32_e32 v4, 14, v113
	s_movk_i32 s8, 0x403
	v_and_or_b32 v121, v3, s8, v4
	v_bfe_u32 v4, v1, 3, 3
	v_and_b32_e32 v2, 63, v1
	v_and_b32_e32 v111, 31, v1
	v_bitop3_b32 v5, v4, v1, 7 bitop3:0x78
	v_lshlrev_b32_e32 v4, 7, v4
	v_and_b32_e32 v3, 7, v1
	v_lshl_or_b32 v106, v5, 4, v4
	v_lshlrev_b32_e32 v4, 7, v111
	v_cmp_lt_u32_e64 s[8:9], 31, v2
	v_bitop3_b32 v2, v113, v1, 7 bitop3:0x78
	v_lshl_or_b32 v154, v2, 4, v4
	v_bitop3_b32 v2, v113, v3, 2 bitop3:0x36
	v_lshl_or_b32 v156, v2, 4, v4
	v_bitop3_b32 v2, v113, v3, 4 bitop3:0x36
	v_lshl_or_b32 v157, v2, 4, v4
	v_bitop3_b32 v2, v113, v3, 6 bitop3:0x36
	v_lshl_or_b32 v158, v2, 4, v4
	v_add_u32_e32 v2, 0x200, v1
	v_mov_b32_e32 v109, 0
	v_lshlrev_b32_e32 v112, 3, v2
	v_lshrrev_b32_e32 v162, 2, v2
	v_lshlrev_b32_e32 v2, 1, v1
	s_movk_i32 s10, 0x80
	v_mov_b32_e32 v107, v109
	v_and_or_b32 v164, v2, s10, v111
	v_lshlrev_b32_e32 v2, 2, v113
	v_lshlrev_b32_e32 v110, 3, v1
	v_lshl_or_b32 v2, v164, 5, v2
	s_add_u32 s97, s66, 0x3c00000
	v_lshl_add_u64 v[4:5], s[66:67], 0, v[106:107]
	s_mov_b64 s[22:23], 0x8000
	s_mov_b32 s0, s3
	v_cmp_gt_u32_e64 s[6:7], 8, v111
	v_lshlrev_b32_e32 v120, 3, v113
	v_or_b32_e32 v122, 0x800, v121
	s_movk_i32 s96, 0x1000
	v_or_b32_e32 v123, 0x1000, v121
	v_or_b32_e32 v124, 0x1800, v121
	v_or_b32_e32 v125, 0x2000, v121
	v_or_b32_e32 v126, 0x2800, v121
	v_or_b32_e32 v127, 0x3000, v121
	v_or_b32_e32 v128, 0x3800, v121
	v_or_b32_e32 v129, 0x8000, v121
	v_or_b32_e32 v130, 0x8800, v121
	v_or_b32_e32 v131, 0x9000, v121
	v_or_b32_e32 v132, 0x9800, v121
	v_or_b32_e32 v133, 0xa000, v121
	v_or_b32_e32 v134, 0xa800, v121
	v_or_b32_e32 v135, 0xb000, v121
	v_or_b32_e32 v136, 0xb800, v121
	v_or_b32_e32 v137, 0x10000, v121
	v_or_b32_e32 v138, 0x10800, v121
	v_or_b32_e32 v139, 0x11000, v121
	v_or_b32_e32 v140, 0x11800, v121
	v_or_b32_e32 v141, 0x12000, v121
	v_or_b32_e32 v142, 0x12800, v121
	v_or_b32_e32 v143, 0x13000, v121
	v_or_b32_e32 v144, 0x13800, v121
	v_or_b32_e32 v145, 0x18000, v121
	v_or_b32_e32 v146, 0x18800, v121
	v_or_b32_e32 v147, 0x19000, v121
	v_or_b32_e32 v148, 0x19800, v121
	v_or_b32_e32 v149, 0x1a000, v121
	v_or_b32_e32 v150, 0x1a800, v121
	v_or_b32_e32 v151, 0x1b000, v121
	v_or_b32_e32 v152, 0x1b800, v121
	v_lshrrev_b32_e32 v153, 6, v1
	v_or_b32_e32 v155, 2, v113
	v_add_u32_e32 v159, 8, v110
	v_lshrrev_b32_e32 v160, 2, v1
	v_add_u32_e32 v161, 8, v112
	v_lshrrev_b32_e32 v163, 7, v1
	s_addc_u32 s3, s67, 0
	v_lshlrev_b32_e32 v165, 1, v111
	s_mov_b32 s21, 0
	v_sub_u32_e32 v166, 0, v111
	v_lshl_add_u64 v[114:115], v[4:5], 0, s[22:23]
	v_lshl_add_u32 v167, v1, 4, 0
	s_movk_i32 s1, 0x100
	s_mov_b32 s74, 0x447fc000
	v_mov_b32_e32 v168, 0xc0447cbd
	s_mov_b32 s75, 0xbfb8aa3b
	s_mov_b32 s76, 0x1a40000
	s_mov_b64 s[24:25], 0x400
	s_mov_b64 s[26:27], 0x800
	s_mov_b64 s[28:29], 0xc00
	s_movk_i32 s77, 0x79c0
	v_mov_b32_e32 v169, 0x4000
	v_mov_b32_e32 v170, 0x7000
	v_mov_b32_e32 v171, 0x5000
	v_mov_b32_e32 v172, 0x8000
	v_lshlrev_b32_e32 v116, 1, v112
	v_mov_b32_e32 v173, 0x3000
	v_mov_b32_e32 v174, 0x6000
	v_lshlrev_b32_e32 v118, 1, v2
	v_mov_b32_e32 v190, v109
	v_mov_b32_e32 v191, v109
	v_mov_b32_e32 v192, v109
	v_mov_b32_e32 v193, v109
	s_mov_b32 s78, s2
	s_mov_b32 s32, s70
	s_cmpk_lg_u32 s70, 0x100
	s_cbranch_scc1 .Lp3_order
	s_bitcmp1_b32 s2, 4
	s_cbranch_scc0 .Lp3_order
	s_addk_i32 s78, 0x100
	s_movk_i32 s32, 0xff00

.LBB0_697:
	s_cmp_lt_i32 s68, 6
	s_cselect_b64 s[6:7], -1, 0
	s_and_b64 s[48:49], s[6:7], s[4:5]
	s_andn2_b64 vcc, exec, s[48:49]
	s_cbranch_vccnz .LBB0_754
	s_cmpk_gt_i32 s2, 0x1ff
	s_cbranch_scc1 .LBB0_754
	v_lshrrev_b32_e32 v83, 8, v1
	s_mov_b32 s5, 0x9600
	v_lshrrev_b32_e32 v2, 1, v1
	v_and_b32_e32 v30, 31, v1
	v_mad_u32_u24 v32, v83, s5, 0
	s_movk_i32 s5, 0x60
	v_bfe_u32 v31, v1, 5, 1
	v_and_or_b32 v38, v2, s5, v30
	v_lshlrev_b32_e32 v134, 4, v31
	s_movk_i32 s8, 0x50
	v_lshlrev_b32_e32 v33, 1, v38
	s_movk_i32 s33, 0x110
	s_movk_i32 s4, 0x100
	v_mad_u32_u24 v135, v38, s8, v32
	v_add_u32_e32 v137, v32, v134
	v_add_u32_e32 v41, v32, v33
	v_mad_u32_u24 v140, v30, s33, v32
	v_lshlrev_b32_e32 v32, 2, v31
	s_add_i32 s42, 0, 0x12c00
	v_cmp_gt_u32_e64 s[4:5], s4, v1
	v_add_u32_e32 v86, s42, v33
	v_xor_b32_e32 v33, 31, v32
	v_cndmask_b32_e64 v143, v33, v32, s[4:5]
	v_or_b32_e32 v33, 2, v32
	v_mov_b32_e32 v2, 0xfffffc00
	v_mov_b32_e32 v3, 0x400
	v_cmp_gt_u32_e64 s[12:13], v33, v30
	v_or_b32_e32 v33, 3, v32
	v_cndmask_b32_e64 v87, v2, v3, s[4:5]
	v_xor_b32_e32 v2, 31, v134
	v_mov_b32_e32 v39, 0xe0
	v_cmp_gt_u32_e64 s[14:15], v33, v30
	v_or_b32_e32 v33, 8, v32
	v_cndmask_b32_e64 v3, v39, 0, s[4:5]
	v_cndmask_b32_e64 v40, v2, v134, s[4:5]
	v_cmp_gt_u32_e64 s[16:17], v33, v30
	v_or_b32_e32 v33, 9, v32
	v_or_b32_e32 v2, v40, v3
	v_cmp_gt_u32_e64 s[18:19], v33, v30
	v_or_b32_e32 v33, 10, v32
	v_lshl_or_b32 v82, v2, 10, v38
	v_cmp_gt_u32_e64 s[20:21], v33, v30
	v_or_b32_e32 v33, 11, v32
	v_add_u32_e32 v84, v82, v87
	v_cmp_gt_u32_e64 s[22:23], v33, v30
	v_or_b32_e32 v33, 16, v32
	v_add_u32_e32 v2, v84, v87
	v_cmp_gt_u32_e64 s[24:25], v33, v30
	v_or_b32_e32 v33, 17, v32
	v_add_u32_e32 v4, v2, v87
	v_cmp_gt_u32_e64 s[26:27], v33, v30
	v_or_b32_e32 v33, 18, v32
	v_add_u32_e32 v6, v4, v87
	v_cmp_gt_u32_e64 s[28:29], v33, v30
	v_or_b32_e32 v33, 19, v32
	v_add_u32_e32 v8, v6, v87
	v_cmp_gt_u32_e64 s[30:31], v33, v30
	v_or_b32_e32 v33, 24, v32
	v_add_u32_e32 v10, v8, v87
	v_cmp_gt_u32_e64 s[34:35], v33, v30
	v_or_b32_e32 v33, 25, v32
	v_add_u32_e32 v12, v10, v87
	v_cmp_gt_u32_e64 s[8:9], v32, v30
	v_cmp_lt_u32_e64 s[10:11], v32, v30
	v_cmp_gt_u32_e64 s[36:37], v33, v30
	v_or_b32_e32 v33, 26, v32
	v_or_b32_e32 v32, 27, v32
	v_mov_b32_e32 v85, 0
	v_add_u32_e32 v14, v12, v87
	v_cmp_gt_u32_e64 s[38:39], v33, v30
	v_cmp_gt_u32_e64 s[40:41], v32, v30
	v_mov_b32_e32 v32, 0x7c00000
	v_mov_b32_e32 v33, 0x5c00000
	v_add_u32_e32 v16, v14, v87
	v_mul_u32_u24_e32 v139, 0x50, v30
	v_mul_u32_u24_e32 v42, 0x110, v30
	v_lshlrev_b32_e32 v30, 3, v1
	v_cndmask_b32_e64 v32, v32, v33, s[4:5]
	v_mov_b32_e32 v33, v85
	v_add_u32_e32 v18, v16, v87
	v_mov_b32_e32 v34, 0xfffffef0
	v_mov_b32_e32 v35, 0x110
	v_and_b32_e32 v44, 0x78, v30
	v_lshl_add_u64 v[88:89], s[66:67], 0, v[32:33]
	v_lshlrev_b32_e32 v32, 2, v38
	v_add_u32_e32 v20, v18, v87
	v_cndmask_b32_e64 v142, v34, v35, s[4:5]
	v_lshlrev_b32_e32 v30, 1, v44
	v_lshl_or_b32 v34, v31, 11, v32
	v_mov_b32_e32 v35, v85
	v_add_u32_e32 v22, v20, v87
	v_cmp_eq_u32_e64 s[6:7], 0, v31
	v_lshlrev_b32_e32 v136, 5, v31
	v_lshlrev_b32_e32 v141, 3, v31
	v_mul_u32_u24_e32 v43, 0x1100, v31
	v_add_u32_e32 v45, s42, v30
	v_lshl_add_u64 v[36:37], s[66:67], 0, v[34:35]
	s_mov_b64 s[42:43], 0x1c00000
	v_cndmask_b32_e64 v31, 0, v39, s[4:5]
	v_add_u32_e32 v24, v22, v87
	s_add_u32 s55, s66, 0x9c00000
	v_lshl_add_u64 v[90:91], v[36:37], 0, s[42:43]
	v_lshl_add_u64 v[32:33], s[66:67], 0, v[32:33]
	s_mov_b64 s[42:43], 0x1b80000
	v_or_b32_e32 v31, v31, v143
	v_mov_b32_e32 v3, v85
	v_add_u32_e32 v26, v24, v87
	v_lshrrev_b32_e32 v159, 4, v1
	s_addc_u32 s57, s67, 0
	v_lshl_add_u64 v[92:93], v[32:33], 0, s[42:43]
	v_mad_u32_u24 v160, v31, s33, v86
	v_lshl_add_u64 v[32:33], s[64:65], 0, v[34:35]
	s_mov_b64 s[42:43], 0x4000000
	v_readlane_b32 s80, v240, 6
	v_mov_b32_e32 v31, v85
	v_mov_b32_e32 v5, v85
	v_mov_b32_e32 v7, v85
	v_mov_b32_e32 v9, v85
	v_mov_b32_e32 v11, v85
	v_mov_b32_e32 v13, v85
	v_mov_b32_e32 v15, v85
	v_mov_b32_e32 v17, v85
	v_mov_b32_e32 v19, v85
	v_mov_b32_e32 v21, v85
	v_mov_b32_e32 v23, v85
	v_mov_b32_e32 v25, v85
	v_mov_b32_e32 v27, v85
	v_add_u32_e32 v28, v26, v87
	v_mov_b32_e32 v29, v85
	v_mul_u32_u24_e32 v46, 0x110, v159
	s_add_u32 s76, s66, 0x3c00000
	v_lshl_add_u64 v[94:95], v[32:33], 0, s[42:43]
	v_lshlrev_b32_e32 v32, 2, v44
	v_mov_b32_e32 v33, v85
	v_readlane_b32 s81, v240, 7
	v_readlane_b32 s82, v240, 8
	v_readlane_b32 s83, v240, 9
	v_readlane_b32 s84, v240, 10
	v_readlane_b32 s85, v240, 11
	v_readlane_b32 s86, v240, 12
	v_readlane_b32 s87, v240, 13
	v_readlane_b32 s88, v240, 14
	v_readlane_b32 s89, v240, 15
	v_readlane_b32 s90, v240, 16
	v_readlane_b32 s91, v240, 17
	v_readlane_b32 s92, v240, 18
	v_readlane_b32 s93, v240, 19
	v_readlane_b32 s94, v240, 20
	v_readlane_b32 s95, v240, 21
	v_lshl_add_u64 v[30:31], s[66:67], 0, v[30:31]
	s_mov_b64 s[42:43], 0xbc00000
	v_lshlrev_b64 v[102:103], 1, v[2:3]
	v_mbcnt_lo_u32_b32 v2, -1, 0
	s_mov_b32 s53, 0
	v_mul_i32_i24_e32 v138, 0xffffffb4, v38
	v_lshlrev_b32_e32 v144, 1, v142
	v_mul_i32_i24_e32 v145, 3, v142
	v_lshlrev_b32_e32 v146, 3, v142
	v_mul_i32_i24_e32 v147, 9, v142
	v_mul_i32_i24_e32 v148, 10, v142
	v_mul_i32_i24_e32 v149, 11, v142
	v_lshlrev_b32_e32 v150, 4, v142
	v_mul_i32_i24_e32 v151, 17, v142
	v_mul_i32_i24_e32 v152, 18, v142
	v_mul_i32_i24_e32 v153, 19, v142
	v_mul_i32_i24_e32 v154, 24, v142
	v_mul_i32_i24_e32 v155, 25, v142
	v_mul_i32_i24_e32 v156, 26, v142
	v_mul_i32_i24_e32 v157, 27, v142
	v_lshlrev_b32_e32 v158, 3, v83
	s_addc_u32 s77, s67, 0
	v_lshl_add_u64 v[96:97], s[82:83], 0, v[32:33]
	v_lshl_add_u64 v[98:99], v[30:31], 0, s[42:43]
	v_lshl_or_b32 v161, v40, 10, v38
	s_movk_i32 s78, 0x2000
	s_movk_i32 s79, 0x3000
	s_movk_i32 s80, 0x4000
	s_movk_i32 s81, 0x5000
	s_movk_i32 s82, 0x6000
	s_movk_i32 s83, 0x7000
	s_mov_b32 s84, 0x8000
	s_mov_b32 s85, 0x9000
	s_mov_b32 s86, 0xa000
	s_mov_b32 s87, 0xb000
	s_mov_b32 s88, 0xc000
	s_mov_b32 s89, 0xd000
	s_mov_b32 s90, 0xe000
	s_mov_b32 s91, 0xf000
	v_add_u32_e32 v162, v45, v46
	s_mov_b32 s92, 0x10000
	s_mov_b32 s93, 0x30000
	s_brev_b32 s54, 60
	s_mov_b32 s56, 0x358637bd
	s_mov_b32 s94, 0x800000
	s_mov_b32 s95, 0x50000
	v_lshlrev_b64 v[100:101], 1, v[84:85]
	v_lshlrev_b64 v[104:105], 1, v[4:5]
	v_lshlrev_b64 v[106:107], 1, v[6:7]
	v_lshlrev_b64 v[108:109], 1, v[8:9]
	v_lshlrev_b64 v[110:111], 1, v[10:11]
	v_lshlrev_b64 v[112:113], 1, v[12:13]
	v_lshlrev_b64 v[114:115], 1, v[14:15]
	v_lshlrev_b64 v[116:117], 1, v[16:17]
	v_lshlrev_b64 v[118:119], 1, v[18:19]
	v_lshlrev_b64 v[120:121], 1, v[20:21]
	v_lshlrev_b64 v[122:123], 1, v[22:23]
	v_lshlrev_b64 v[124:125], 1, v[24:25]
	v_lshlrev_b64 v[126:127], 1, v[26:27]
	v_lshlrev_b64 v[128:129], 1, v[28:29]
	v_mbcnt_hi_u32_b32 v163, -1, v2
	v_add_u32_e32 v164, v41, v43
	v_add_u32_e32 v165, v137, v42
	s_mov_b32 s96, s2
	s_mov_b32 s32, s70
	s_cmpk_lg_u32 s70, 0x100
	s_cbranch_scc1 .Lp5_order
	s_bitcmp1_b32 s2, 4
	s_cbranch_scc0 .Lp5_order
	s_addk_i32 s96, 0x100
	s_movk_i32 s32, 0xff00
